# P3 queue order: heavy attention, conv, light attention, weight copies last (copies as tail filler), on p3d
# speedup vs baseline: 1.0019x; 1.0009x over previous
; template<int THRL,class Extra> __device__ __forceinline__ void attn_phase_dyn(char*lds,const AttnTensors&T,unsigned*ctr,const Extra&X,int nextra){
;     ...
;   for(;;){
;     if(tid==0){uw[0]=nxt;}
;     asm volatile("s_waitcnt lgkmcnt(0)\n\ts_barrier":::"memory");
;     const unsigned u=(unsigned)__builtin_amdgcn_readfirstlane((int)uw[0]);
;     if(u>=(unsigned)(BATCH*NHEAD*NQB+nextra))break;
;     if(u>=(unsigned)(BATCH*NHEAD*NQB)){ if(tid==0)nxt=G_+__hip_atomic_fetch_add(ctr,1u,__ATOMIC_RELAXED,__HIP_MEMORY_SCOPE_AGENT);
;       X((int)u-BATCH*NHEAD*NQB); asm volatile("s_waitcnt lgkmcnt(0)\n\ts_barrier":::"memory"); continue; }
;     const int qb=NQB-1-(int)(u/(BATCH*NHEAD)), bh=(int)(u%(BATCH*NHEAD));
.LBB0_343:
	s_and_saveexec_b64 s[6:7], s[18:19]
	ds_write_b32 v201, v213 offset:49152
	s_or_b64 exec, exec, s[6:7]
	s_waitcnt lgkmcnt(0)
	s_barrier
	ds_read_b32 v1, v201 offset:49152
	s_mov_b64 s[6:7], -1
	s_waitcnt lgkmcnt(0)
	v_readfirstlane_b32 s63, v1
	s_cmpk_lt_u32 s63, 0x300
	s_cbranch_scc1 .Lqmap_done
	s_cmpk_gt_u32 s63, 0x4ff
	s_cbranch_scc1 .Lqmap_done
	s_add_i32 s80, s63, 0x100
	s_cmpk_lt_u32 s63, 0x400
	s_cbranch_scc1 .Lqmap_set
	s_add_i32 s80, s63, 0xffffff00
